# FFN2-down epilogue fused with the final RMSNorm, deterministic row-sum combination (LDS exchange + per-workgroup slots, fixed add order); final-norm phase and its grid barrier removed
# speedup vs baseline: 1.0184x; 1.0053x over previous
.LBB0_1270:
	s_or_b64 exec, exec, s[0:1]
	s_lshl_b32 s0, s87, 9
	v_add_u32_e32 v0, s0, v230
	v_mov_b32_e32 v1, 0x100
	v_cmp_gt_u32_e32 vcc, v1, v0
	s_and_saveexec_b64 s[2:3], vcc
	s_load_dwordx2 s[0:1], s[92:93], 0xd8
	v_lshlrev_b32_e32 v0, 2, v0
	v_mov_b32_e32 v1, 0
	s_waitcnt lgkmcnt(0)
	s_add_u32 s0, s0, 0x33a0000
	s_addc_u32 s1, s1, 0
	global_store_dword v0, v1, s[0:1]
	s_or_b64 exec, exec, s[2:3]
	s_waitcnt vmcnt(0)
	s_barrier
	s_mov_b64 s[0:1], exec
	v_readlane_b32 s2, v252, 2
	v_readlane_b32 s3, v252, 3
	s_and_b64 s[2:3], s[0:1], s[2:3]
	s_mov_b64 exec, s[2:3]
	s_cbranch_execz .LBB0_1322
	s_add_i32 s2, 0, 0x20040
	v_mov_b32_e32 v0, s2
	s_waitcnt vmcnt(0) expcnt(0) lgkmcnt(0)
	ds_read_b32 v2, v0
	s_add_i32 s2, 0, 0x20044
	v_mov_b32_e32 v0, s2
	ds_read_b32 v0, v0
	s_waitcnt lgkmcnt(1)
	v_cmp_ne_u32_e32 vcc, 0, v2
	s_cbranch_vccnz .LBB0_1286
	s_add_u32 s6, s88, 0x1000
	s_addc_u32 s7, s89, 0
	s_add_u32 s8, s88, 0x1100
	s_addc_u32 s9, s89, 0
	s_add_u32 s10, s88, 0x1200
	v_readlane_b32 s2, v252, 0
	s_addc_u32 s11, s89, 0
	s_mul_i32 s2, s91, s2
	s_add_u32 s12, s88, 0x1300
	s_mul_i32 s2, s2, s90
	s_addc_u32 s13, s89, 0
	s_mov_b32 s3, 1
	v_mov_b32_e32 v16, 0
	s_branch .LBB0_1274

.LBB0_1414:
	v_lshl_add_u32 v128, s66, 8, v218
	v_lshl_or_b32 v136, s67, 8, v220
	s_load_dwordx2 s[18:19], s[92:93], 0xc8
	s_load_dwordx2 s[20:21], s[92:93], 0xd8
	s_ashr_i32 s2, s66, 4
	v_lshlrev_b32_e32 v137, 2, v128
	v_lshlrev_b32_e32 v136, 2, v136
	s_mul_hi_i32 s31, s2, 0x9000
	s_mul_i32 s2, s2, 0x9000
	v_lshl_add_u32 v128, v128, 12, v136
	s_add_u32 s30, s50, s2
	s_addc_u32 s31, s51, s31
	v_add_u32_e32 v129, 0x10000, v128
	v_add_u32_e32 v130, 0x20000, v128
	v_add_u32_e32 v131, 0x30000, v128
	v_add_u32_e32 v132, 0x80000, v128
	v_add_u32_e32 v133, 0x90000, v128
	v_add_u32_e32 v134, 0xa0000, v128
	v_add_u32_e32 v135, 0xb0000, v128
	v_and_b32_e32 v138, 63, v230
	v_xor_b32_e32 v139, 32, v138
	v_xor_b32_e32 v138, 16, v138
	v_lshlrev_b32_e32 v139, 2, v139
	v_lshlrev_b32_e32 v138, 2, v138
	global_load_dwordx4 v[140:143], v136, s[30:31]
	global_load_dwordx4 v[144:147], v136, s[30:31] offset:64
	global_load_dwordx4 v[148:151], v136, s[30:31] offset:512
	global_load_dwordx4 v[152:155], v136, s[30:31] offset:576
	global_load_dwordx4 v[184:187], v128, s[8:9]
	global_load_dwordx4 v[188:191], v128, s[8:9] offset:64
	global_load_dwordx4 v[192:195], v128, s[8:9] offset:512
	global_load_dwordx4 v[196:199], v128, s[8:9] offset:576
	global_load_dwordx4 v[200:203], v129, s[8:9]
	global_load_dwordx4 v[204:207], v129, s[8:9] offset:64
	global_load_dwordx4 v[208:211], v129, s[8:9] offset:512
	global_load_dwordx4 v[212:215], v129, s[8:9] offset:576
	global_load_dwordx4 v[156:159], v130, s[8:9]
	global_load_dwordx4 v[160:163], v130, s[8:9] offset:64
	global_load_dwordx4 v[164:167], v130, s[8:9] offset:512
	global_load_dwordx4 v[168:171], v130, s[8:9] offset:576
	global_load_dwordx4 v[232:235], v131, s[8:9]
	global_load_dwordx4 v[236:239], v131, s[8:9] offset:64
	global_load_dwordx4 v[240:243], v131, s[8:9] offset:512
	global_load_dwordx4 v[244:247], v131, s[8:9] offset:576
	s_waitcnt lgkmcnt(0)
	s_add_u32 s20, s20, 0x32a0000
	s_addc_u32 s21, s21, 0
	s_add_u32 s22, s20, 0x100000
	s_addc_u32 s23, s21, 0
	s_waitcnt vmcnt(8)
	v_pk_mul_f32 v[140:141], v[140:141], 0.5 op_sel_hi:[1,0]
	v_pk_mul_f32 v[142:143], v[142:143], 0.5 op_sel_hi:[1,0]
	v_pk_mul_f32 v[144:145], v[144:145], 0.5 op_sel_hi:[1,0]
	v_pk_mul_f32 v[146:147], v[146:147], 0.5 op_sel_hi:[1,0]
	v_pk_mul_f32 v[148:149], v[148:149], 0.5 op_sel_hi:[1,0]
	v_pk_mul_f32 v[150:151], v[150:151], 0.5 op_sel_hi:[1,0]
	v_pk_mul_f32 v[152:153], v[152:153], 0.5 op_sel_hi:[1,0]
	v_pk_mul_f32 v[154:155], v[154:155], 0.5 op_sel_hi:[1,0]
	v_pk_fma_f32 v[124:125], v[124:125], v[140:141], v[184:185]
	v_pk_fma_f32 v[126:127], v[126:127], v[142:143], v[186:187]
	v_pk_mul_f32 v[216:217], v[124:125], v[124:125]
	v_pk_fma_f32 v[216:217], v[126:127], v[126:127], v[216:217]
	v_pk_fma_f32 v[96:97], v[96:97], v[144:145], v[188:189]
	v_pk_fma_f32 v[98:99], v[98:99], v[146:147], v[190:191]
	v_pk_fma_f32 v[216:217], v[96:97], v[96:97], v[216:217]
	v_pk_fma_f32 v[216:217], v[98:99], v[98:99], v[216:217]
	v_pk_fma_f32 v[64:65], v[64:65], v[148:149], v[192:193]
	v_pk_fma_f32 v[66:67], v[66:67], v[150:151], v[194:195]
	v_pk_fma_f32 v[216:217], v[64:65], v[64:65], v[216:217]
	v_pk_fma_f32 v[216:217], v[66:67], v[66:67], v[216:217]
	v_pk_fma_f32 v[44:45], v[44:45], v[152:153], v[196:197]
	v_pk_fma_f32 v[46:47], v[46:47], v[154:155], v[198:199]
	v_pk_fma_f32 v[216:217], v[44:45], v[44:45], v[216:217]
	v_pk_fma_f32 v[216:217], v[46:47], v[46:47], v[216:217]
	s_nop 0
	v_add_f32_e32 v224, v216, v217
	v_pk_fma_f32 v[120:121], v[120:121], v[140:141], v[200:201]
	v_pk_fma_f32 v[122:123], v[122:123], v[142:143], v[202:203]
	v_pk_mul_f32 v[216:217], v[120:121], v[120:121]
	v_pk_fma_f32 v[216:217], v[122:123], v[122:123], v[216:217]
	v_pk_fma_f32 v[88:89], v[88:89], v[144:145], v[204:205]
	v_pk_fma_f32 v[90:91], v[90:91], v[146:147], v[206:207]
	v_pk_fma_f32 v[216:217], v[88:89], v[88:89], v[216:217]
	v_pk_fma_f32 v[216:217], v[90:91], v[90:91], v[216:217]
	v_pk_fma_f32 v[56:57], v[56:57], v[148:149], v[208:209]
	v_pk_fma_f32 v[58:59], v[58:59], v[150:151], v[210:211]
	v_pk_fma_f32 v[216:217], v[56:57], v[56:57], v[216:217]
	v_pk_fma_f32 v[216:217], v[58:59], v[58:59], v[216:217]
	v_pk_fma_f32 v[36:37], v[36:37], v[152:153], v[212:213]
	v_pk_fma_f32 v[38:39], v[38:39], v[154:155], v[214:215]
	v_pk_fma_f32 v[216:217], v[36:37], v[36:37], v[216:217]
	v_pk_fma_f32 v[216:217], v[38:39], v[38:39], v[216:217]
	s_nop 0
	v_add_f32_e32 v225, v216, v217
	s_nop 1
	global_load_dwordx4 v[184:187], v132, s[8:9]
	global_load_dwordx4 v[188:191], v132, s[8:9] offset:64
	global_load_dwordx4 v[192:195], v132, s[8:9] offset:512
	global_load_dwordx4 v[196:199], v132, s[8:9] offset:576
	global_load_dwordx4 v[200:203], v133, s[8:9]
	global_load_dwordx4 v[204:207], v133, s[8:9] offset:64
	global_load_dwordx4 v[208:211], v133, s[8:9] offset:512
	global_load_dwordx4 v[212:215], v133, s[8:9] offset:576
	s_waitcnt vmcnt(8)
	v_pk_fma_f32 v[116:117], v[116:117], v[140:141], v[156:157]
	v_pk_fma_f32 v[118:119], v[118:119], v[142:143], v[158:159]
	v_pk_mul_f32 v[216:217], v[116:117], v[116:117]
	v_pk_fma_f32 v[216:217], v[118:119], v[118:119], v[216:217]
	v_pk_fma_f32 v[84:85], v[84:85], v[144:145], v[160:161]
	v_pk_fma_f32 v[86:87], v[86:87], v[146:147], v[162:163]
	v_pk_fma_f32 v[216:217], v[84:85], v[84:85], v[216:217]
	v_pk_fma_f32 v[216:217], v[86:87], v[86:87], v[216:217]
	v_pk_fma_f32 v[52:53], v[52:53], v[148:149], v[164:165]
	v_pk_fma_f32 v[54:55], v[54:55], v[150:151], v[166:167]
	v_pk_fma_f32 v[216:217], v[52:53], v[52:53], v[216:217]
	v_pk_fma_f32 v[216:217], v[54:55], v[54:55], v[216:217]
	v_pk_fma_f32 v[28:29], v[28:29], v[152:153], v[168:169]
	v_pk_fma_f32 v[30:31], v[30:31], v[154:155], v[170:171]
	v_pk_fma_f32 v[216:217], v[28:29], v[28:29], v[216:217]
	v_pk_fma_f32 v[216:217], v[30:31], v[30:31], v[216:217]
	s_nop 0
	v_add_f32_e32 v226, v216, v217
	v_pk_fma_f32 v[112:113], v[112:113], v[140:141], v[232:233]
	v_pk_fma_f32 v[114:115], v[114:115], v[142:143], v[234:235]
	v_pk_mul_f32 v[216:217], v[112:113], v[112:113]
	v_pk_fma_f32 v[216:217], v[114:115], v[114:115], v[216:217]
	v_pk_fma_f32 v[80:81], v[80:81], v[144:145], v[236:237]
	v_pk_fma_f32 v[82:83], v[82:83], v[146:147], v[238:239]
	v_pk_fma_f32 v[216:217], v[80:81], v[80:81], v[216:217]
	v_pk_fma_f32 v[216:217], v[82:83], v[82:83], v[216:217]
	v_pk_fma_f32 v[48:49], v[48:49], v[148:149], v[240:241]
	v_pk_fma_f32 v[50:51], v[50:51], v[150:151], v[242:243]
	v_pk_fma_f32 v[216:217], v[48:49], v[48:49], v[216:217]
	v_pk_fma_f32 v[216:217], v[50:51], v[50:51], v[216:217]
	v_pk_fma_f32 v[20:21], v[20:21], v[152:153], v[244:245]
	v_pk_fma_f32 v[22:23], v[22:23], v[154:155], v[246:247]
	v_pk_fma_f32 v[216:217], v[20:21], v[20:21], v[216:217]
	v_pk_fma_f32 v[216:217], v[22:23], v[22:23], v[216:217]
	s_nop 0
	v_add_f32_e32 v227, v216, v217
	s_nop 1
	global_load_dwordx4 v[156:159], v134, s[8:9]
	global_load_dwordx4 v[160:163], v134, s[8:9] offset:64
	global_load_dwordx4 v[164:167], v134, s[8:9] offset:512
	global_load_dwordx4 v[168:171], v134, s[8:9] offset:576
	global_load_dwordx4 v[232:235], v135, s[8:9]
	global_load_dwordx4 v[236:239], v135, s[8:9] offset:64
	global_load_dwordx4 v[240:243], v135, s[8:9] offset:512
	global_load_dwordx4 v[244:247], v135, s[8:9] offset:576
	s_waitcnt vmcnt(8)
	v_pk_fma_f32 v[108:109], v[108:109], v[140:141], v[184:185]
	v_pk_fma_f32 v[110:111], v[110:111], v[142:143], v[186:187]
	v_pk_mul_f32 v[216:217], v[108:109], v[108:109]
	v_pk_fma_f32 v[216:217], v[110:111], v[110:111], v[216:217]
	v_pk_fma_f32 v[76:77], v[76:77], v[144:145], v[188:189]
	v_pk_fma_f32 v[78:79], v[78:79], v[146:147], v[190:191]
	v_pk_fma_f32 v[216:217], v[76:77], v[76:77], v[216:217]
	v_pk_fma_f32 v[216:217], v[78:79], v[78:79], v[216:217]
	v_pk_fma_f32 v[40:41], v[40:41], v[148:149], v[192:193]
	v_pk_fma_f32 v[42:43], v[42:43], v[150:151], v[194:195]
	v_pk_fma_f32 v[216:217], v[40:41], v[40:41], v[216:217]
	v_pk_fma_f32 v[216:217], v[42:43], v[42:43], v[216:217]
	v_pk_fma_f32 v[12:13], v[12:13], v[152:153], v[196:197]
	v_pk_fma_f32 v[14:15], v[14:15], v[154:155], v[198:199]
	v_pk_fma_f32 v[216:217], v[12:13], v[12:13], v[216:217]
	v_pk_fma_f32 v[216:217], v[14:15], v[14:15], v[216:217]
	s_nop 0
	v_add_f32_e32 v228, v216, v217
	v_pk_fma_f32 v[104:105], v[104:105], v[140:141], v[200:201]
	v_pk_fma_f32 v[106:107], v[106:107], v[142:143], v[202:203]
	v_pk_mul_f32 v[216:217], v[104:105], v[104:105]
	v_pk_fma_f32 v[216:217], v[106:107], v[106:107], v[216:217]
	v_pk_fma_f32 v[72:73], v[72:73], v[144:145], v[204:205]
	v_pk_fma_f32 v[74:75], v[74:75], v[146:147], v[206:207]
	v_pk_fma_f32 v[216:217], v[72:73], v[72:73], v[216:217]
	v_pk_fma_f32 v[216:217], v[74:75], v[74:75], v[216:217]
	v_pk_fma_f32 v[32:33], v[32:33], v[148:149], v[208:209]
	v_pk_fma_f32 v[34:35], v[34:35], v[150:151], v[210:211]
	v_pk_fma_f32 v[216:217], v[32:33], v[32:33], v[216:217]
	v_pk_fma_f32 v[216:217], v[34:35], v[34:35], v[216:217]
	v_pk_fma_f32 v[8:9], v[8:9], v[152:153], v[212:213]
	v_pk_fma_f32 v[10:11], v[10:11], v[154:155], v[214:215]
	v_pk_fma_f32 v[216:217], v[8:9], v[8:9], v[216:217]
	v_pk_fma_f32 v[216:217], v[10:11], v[10:11], v[216:217]
	s_nop 0
	v_add_f32_e32 v229, v216, v217
	s_nop 1
	global_load_dwordx4 v[184:187], v136, s[18:19]
	global_load_dwordx4 v[188:191], v136, s[18:19] offset:64
	global_load_dwordx4 v[192:195], v136, s[18:19] offset:512
	global_load_dwordx4 v[196:199], v136, s[18:19] offset:576
	s_waitcnt vmcnt(4)
	v_pk_fma_f32 v[100:101], v[100:101], v[140:141], v[156:157]
	v_pk_fma_f32 v[102:103], v[102:103], v[142:143], v[158:159]
	v_pk_mul_f32 v[216:217], v[100:101], v[100:101]
	v_pk_fma_f32 v[216:217], v[102:103], v[102:103], v[216:217]
	v_pk_fma_f32 v[68:69], v[68:69], v[144:145], v[160:161]
	v_pk_fma_f32 v[70:71], v[70:71], v[146:147], v[162:163]
	v_pk_fma_f32 v[216:217], v[68:69], v[68:69], v[216:217]
	v_pk_fma_f32 v[216:217], v[70:71], v[70:71], v[216:217]
	v_pk_fma_f32 v[24:25], v[24:25], v[148:149], v[164:165]
	v_pk_fma_f32 v[26:27], v[26:27], v[150:151], v[166:167]
	v_pk_fma_f32 v[216:217], v[24:25], v[24:25], v[216:217]
	v_pk_fma_f32 v[216:217], v[26:27], v[26:27], v[216:217]
	v_pk_fma_f32 v[4:5], v[4:5], v[152:153], v[168:169]
	v_pk_fma_f32 v[6:7], v[6:7], v[154:155], v[170:171]
	v_pk_fma_f32 v[216:217], v[4:5], v[4:5], v[216:217]
	v_pk_fma_f32 v[216:217], v[6:7], v[6:7], v[216:217]
	s_nop 0
	v_add_f32_e32 v248, v216, v217
	v_pk_fma_f32 v[92:93], v[92:93], v[140:141], v[232:233]
	v_pk_fma_f32 v[94:95], v[94:95], v[142:143], v[234:235]
	v_pk_mul_f32 v[216:217], v[92:93], v[92:93]
	v_pk_fma_f32 v[216:217], v[94:95], v[94:95], v[216:217]
	v_pk_fma_f32 v[60:61], v[60:61], v[144:145], v[236:237]
	v_pk_fma_f32 v[62:63], v[62:63], v[146:147], v[238:239]
	v_pk_fma_f32 v[216:217], v[60:61], v[60:61], v[216:217]
	v_pk_fma_f32 v[216:217], v[62:63], v[62:63], v[216:217]
	v_pk_fma_f32 v[16:17], v[16:17], v[148:149], v[240:241]
	v_pk_fma_f32 v[18:19], v[18:19], v[150:151], v[242:243]
	v_pk_fma_f32 v[216:217], v[16:17], v[16:17], v[216:217]
	v_pk_fma_f32 v[216:217], v[18:19], v[18:19], v[216:217]
	v_pk_fma_f32 v[0:1], v[0:1], v[152:153], v[244:245]
	v_pk_fma_f32 v[2:3], v[2:3], v[154:155], v[246:247]
	v_pk_fma_f32 v[216:217], v[0:1], v[0:1], v[216:217]
	v_pk_fma_f32 v[216:217], v[2:3], v[2:3], v[216:217]
	s_nop 0
	v_add_f32_e32 v249, v216, v217
	ds_bpermute_b32 v200, v138, v224
	ds_bpermute_b32 v201, v138, v225
	ds_bpermute_b32 v202, v138, v226
	ds_bpermute_b32 v203, v138, v227
	ds_bpermute_b32 v204, v138, v228
	ds_bpermute_b32 v205, v138, v229
	ds_bpermute_b32 v206, v138, v248
	ds_bpermute_b32 v207, v138, v249
	s_waitcnt lgkmcnt(0)
	v_add_f32_e32 v224, v224, v200
	v_add_f32_e32 v225, v225, v201
	v_add_f32_e32 v226, v226, v202
	v_add_f32_e32 v227, v227, v203
	v_add_f32_e32 v228, v228, v204
	v_add_f32_e32 v229, v229, v205
	v_add_f32_e32 v248, v248, v206
	v_add_f32_e32 v249, v249, v207
	ds_bpermute_b32 v200, v139, v224
	ds_bpermute_b32 v201, v139, v225
	ds_bpermute_b32 v202, v139, v226
	ds_bpermute_b32 v203, v139, v227
	ds_bpermute_b32 v204, v139, v228
	ds_bpermute_b32 v205, v139, v229
	ds_bpermute_b32 v206, v139, v248
	ds_bpermute_b32 v207, v139, v249
	s_waitcnt lgkmcnt(0)
	v_add_f32_e32 v224, v224, v200
	v_add_f32_e32 v225, v225, v201
	v_add_f32_e32 v226, v226, v202
	v_add_f32_e32 v227, v227, v203
	v_add_f32_e32 v228, v228, v204
	v_add_f32_e32 v229, v229, v205
	v_add_f32_e32 v248, v248, v206
	v_add_f32_e32 v249, v249, v207
	v_lshrrev_b32_e32 v140, 5, v220
	v_and_b32_e32 v140, 3, v140
	v_lshlrev_b32_e32 v142, 4, v218
	v_add_u32_e32 v142, 0x20400, v142
	v_lshl_add_u32 v141, v140, 2, v142
	v_lshl_add_u32 v144, s66, 8, v218
	v_lshlrev_b32_e32 v144, 4, v144
	v_mov_b32_e32 v143, s67
	v_lshl_add_u32 v143, v143, 2, v144
	s_mov_b64 exec, 0xffff
	ds_write_b32 v141, v224
	ds_write_b32 v141, v225 offset:256
	ds_write_b32 v141, v226 offset:512
	ds_write_b32 v141, v227 offset:768
	ds_write_b32 v141, v228 offset:2048
	ds_write_b32 v141, v229 offset:2304
	ds_write_b32 v141, v248 offset:2560
	ds_write_b32 v141, v249 offset:2816
	s_mov_b64 exec, -1
	s_waitcnt lgkmcnt(0)
	s_barrier
	ds_read_b128 v[156:159], v142
	ds_read_b128 v[160:163], v142 offset:256
	ds_read_b128 v[164:167], v142 offset:512
	ds_read_b128 v[168:171], v142 offset:768
	ds_read_b128 v[232:235], v142 offset:2048
	ds_read_b128 v[236:239], v142 offset:2304
	ds_read_b128 v[240:243], v142 offset:2560
	ds_read_b128 v[244:247], v142 offset:2816
	s_waitcnt lgkmcnt(0)
	v_add_f32_e32 v250, v156, v157
	v_add_f32_e32 v251, v158, v159
	v_add_f32_e32 v224, v250, v251
	v_add_f32_e32 v250, v160, v161
	v_add_f32_e32 v251, v162, v163
	v_add_f32_e32 v225, v250, v251
	v_add_f32_e32 v250, v164, v165
	v_add_f32_e32 v251, v166, v167
	v_add_f32_e32 v226, v250, v251
	v_add_f32_e32 v250, v168, v169
	v_add_f32_e32 v251, v170, v171
	v_add_f32_e32 v227, v250, v251
	v_add_f32_e32 v250, v232, v233
	v_add_f32_e32 v251, v234, v235
	v_add_f32_e32 v228, v250, v251
	v_add_f32_e32 v250, v236, v237
	v_add_f32_e32 v251, v238, v239
	v_add_f32_e32 v229, v250, v251
	v_add_f32_e32 v250, v240, v241
	v_add_f32_e32 v251, v242, v243
	v_add_f32_e32 v248, v250, v251
	v_add_f32_e32 v250, v244, v245
	v_add_f32_e32 v251, v246, v247
	v_add_f32_e32 v249, v250, v251
	v_readfirstlane_b32 s26, v140
	s_nop 0
	s_cmp_lg_u32 s26, 0
	s_cbranch_scc1 .Lfn_nosw_p14
	s_mov_b64 exec, 0xffff
	global_atomic_swap v143, v224, s[20:21]
	global_atomic_swap v143, v225, s[20:21] offset:256
	global_atomic_swap v143, v226, s[20:21] offset:512
	global_atomic_swap v143, v227, s[20:21] offset:768
	global_atomic_swap v143, v228, s[20:21] offset:2048
	global_atomic_swap v143, v229, s[20:21] offset:2304
	global_atomic_swap v143, v248, s[20:21] offset:2560
	global_atomic_swap v143, v249, s[20:21] offset:2816
	s_mov_b64 exec, -1
.Lfn_nosw_p14:
	s_waitcnt vmcnt(0)
	s_barrier
	v_cmp_eq_u32_e32 vcc, 0, v230
	s_and_saveexec_b64 s[24:25], vcc
	s_cbranch_execz .Lfn_meet_p14
	s_lshl_b32 s26, s66, 2
	v_mov_b32_e32 v250, 1
	v_mov_b32_e32 v251, s26
	s_mov_b32 s27, 0
	global_atomic_add v251, v250, s[22:23]

.Lfn_meet_p14:
	s_or_b64 exec, exec, s[24:25]
	s_barrier
	global_load_dwordx4 v[156:159], v144, s[20:21] sc1
	global_load_dwordx4 v[160:163], v144, s[20:21] offset:256 sc1
	global_load_dwordx4 v[164:167], v144, s[20:21] offset:512 sc1
	global_load_dwordx4 v[168:171], v144, s[20:21] offset:768 sc1
	global_load_dwordx4 v[232:235], v144, s[20:21] offset:2048 sc1
	global_load_dwordx4 v[236:239], v144, s[20:21] offset:2304 sc1
	global_load_dwordx4 v[240:243], v144, s[20:21] offset:2560 sc1
	global_load_dwordx4 v[244:247], v144, s[20:21] offset:2816 sc1
	s_waitcnt vmcnt(0)
	v_add_f32_e32 v250, v156, v157
	v_add_f32_e32 v251, v158, v159
	v_add_f32_e32 v146, v250, v251
	v_add_f32_e32 v250, v160, v161
	v_add_f32_e32 v251, v162, v163
	v_add_f32_e32 v147, v250, v251
	v_add_f32_e32 v250, v164, v165
	v_add_f32_e32 v251, v166, v167
	v_add_f32_e32 v148, v250, v251
	v_add_f32_e32 v250, v168, v169
	v_add_f32_e32 v251, v170, v171
	v_add_f32_e32 v149, v250, v251
	v_add_f32_e32 v250, v232, v233
	v_add_f32_e32 v251, v234, v235
	v_add_f32_e32 v150, v250, v251
	v_add_f32_e32 v250, v236, v237
	v_add_f32_e32 v251, v238, v239
	v_add_f32_e32 v151, v250, v251
	v_add_f32_e32 v250, v240, v241
	v_add_f32_e32 v251, v242, v243
	v_add_f32_e32 v152, v250, v251
	v_add_f32_e32 v250, v244, v245
	v_add_f32_e32 v251, v246, v247
	v_add_f32_e32 v153, v250, v251
	v_mov_b32_e32 v216, 0x358637bd
	v_mov_b32_e32 v217, 0x260
	s_mov_b32 s16, 0xf800000
	v_fmamk_f32 v146, v146, 0x3a800000, v216
	v_mul_f32_e32 v156, 0x4f800000, v146
	v_cmp_gt_f32_e32 vcc, s16, v146
	s_nop 1
	v_cndmask_b32_e32 v146, v146, v156, vcc
	v_sqrt_f32_e32 v157, v146
	s_nop 1
	v_add_u32_e32 v158, -1, v157
	v_add_u32_e32 v159, 1, v157
	v_fma_f32 v160, -v158, v157, v146
	v_fma_f32 v161, -v159, v157, v146
	v_cmp_ge_f32_e64 s[26:27], 0, v160
	s_nop 1
	v_cndmask_b32_e64 v157, v157, v158, s[26:27]
	v_cmp_lt_f32_e64 s[26:27], 0, v161
	s_nop 1
	v_cndmask_b32_e64 v157, v157, v159, s[26:27]
	v_mul_f32_e32 v158, 0x37800000, v157
	v_cndmask_b32_e32 v157, v157, v158, vcc
	v_cmp_class_f32_e32 vcc, v146, v217
	s_nop 1
	v_cndmask_b32_e32 v146, v157, v146, vcc
	v_div_scale_f32 v156, s[26:27], v146, v146, 1.0
	v_rcp_f32_e32 v157, v156
	v_div_scale_f32 v158, vcc, 1.0, v146, 1.0
	v_fma_f32 v159, -v156, v157, 1.0
	v_fmac_f32_e32 v157, v159, v157
	v_mul_f32_e32 v159, v158, v157
	v_fma_f32 v160, -v156, v159, v158
	v_fmac_f32_e32 v159, v160, v157
	v_fma_f32 v156, -v156, v159, v158
	v_div_fmas_f32 v159, v156, v157, v159
	v_div_fixup_f32 v200, v159, v146, 1.0
	v_fmamk_f32 v147, v147, 0x3a800000, v216
	v_mul_f32_e32 v156, 0x4f800000, v147
	v_cmp_gt_f32_e32 vcc, s16, v147
	s_nop 1
	v_cndmask_b32_e32 v147, v147, v156, vcc
	v_sqrt_f32_e32 v157, v147
	s_nop 1
	v_add_u32_e32 v158, -1, v157
	v_add_u32_e32 v159, 1, v157
	v_fma_f32 v160, -v158, v157, v147
	v_fma_f32 v161, -v159, v157, v147
	v_cmp_ge_f32_e64 s[26:27], 0, v160
	s_nop 1
	v_cndmask_b32_e64 v157, v157, v158, s[26:27]
	v_cmp_lt_f32_e64 s[26:27], 0, v161
	s_nop 1
	v_cndmask_b32_e64 v157, v157, v159, s[26:27]
	v_mul_f32_e32 v158, 0x37800000, v157
	v_cndmask_b32_e32 v157, v157, v158, vcc
	v_cmp_class_f32_e32 vcc, v147, v217
	s_nop 1
	v_cndmask_b32_e32 v147, v157, v147, vcc
	v_div_scale_f32 v156, s[26:27], v147, v147, 1.0
	v_rcp_f32_e32 v157, v156
	v_div_scale_f32 v158, vcc, 1.0, v147, 1.0
	v_fma_f32 v159, -v156, v157, 1.0
	v_fmac_f32_e32 v157, v159, v157
	v_mul_f32_e32 v159, v158, v157
	v_fma_f32 v160, -v156, v159, v158
	v_fmac_f32_e32 v159, v160, v157
	v_fma_f32 v156, -v156, v159, v158
	v_div_fmas_f32 v159, v156, v157, v159
	v_div_fixup_f32 v202, v159, v147, 1.0
	v_fmamk_f32 v148, v148, 0x3a800000, v216
	v_mul_f32_e32 v156, 0x4f800000, v148
	v_cmp_gt_f32_e32 vcc, s16, v148
	s_nop 1
	v_cndmask_b32_e32 v148, v148, v156, vcc
	v_sqrt_f32_e32 v157, v148
	s_nop 1
	v_add_u32_e32 v158, -1, v157
	v_add_u32_e32 v159, 1, v157
	v_fma_f32 v160, -v158, v157, v148
	v_fma_f32 v161, -v159, v157, v148
	v_cmp_ge_f32_e64 s[26:27], 0, v160
	s_nop 1
	v_cndmask_b32_e64 v157, v157, v158, s[26:27]
	v_cmp_lt_f32_e64 s[26:27], 0, v161
	s_nop 1
	v_cndmask_b32_e64 v157, v157, v159, s[26:27]
	v_mul_f32_e32 v158, 0x37800000, v157
	v_cndmask_b32_e32 v157, v157, v158, vcc
	v_cmp_class_f32_e32 vcc, v148, v217
	s_nop 1
	v_cndmask_b32_e32 v148, v157, v148, vcc
	v_div_scale_f32 v156, s[26:27], v148, v148, 1.0
	v_rcp_f32_e32 v157, v156
	v_div_scale_f32 v158, vcc, 1.0, v148, 1.0
	v_fma_f32 v159, -v156, v157, 1.0
	v_fmac_f32_e32 v157, v159, v157
	v_mul_f32_e32 v159, v158, v157
	v_fma_f32 v160, -v156, v159, v158
	v_fmac_f32_e32 v159, v160, v157
	v_fma_f32 v156, -v156, v159, v158
	v_div_fmas_f32 v159, v156, v157, v159
	v_div_fixup_f32 v204, v159, v148, 1.0
	v_fmamk_f32 v149, v149, 0x3a800000, v216
	v_mul_f32_e32 v156, 0x4f800000, v149
	v_cmp_gt_f32_e32 vcc, s16, v149
	s_nop 1
	v_cndmask_b32_e32 v149, v149, v156, vcc
	v_sqrt_f32_e32 v157, v149
	s_nop 1
	v_add_u32_e32 v158, -1, v157
	v_add_u32_e32 v159, 1, v157
	v_fma_f32 v160, -v158, v157, v149
	v_fma_f32 v161, -v159, v157, v149
	v_cmp_ge_f32_e64 s[26:27], 0, v160
	s_nop 1
	v_cndmask_b32_e64 v157, v157, v158, s[26:27]
	v_cmp_lt_f32_e64 s[26:27], 0, v161
	s_nop 1
	v_cndmask_b32_e64 v157, v157, v159, s[26:27]
	v_mul_f32_e32 v158, 0x37800000, v157
	v_cndmask_b32_e32 v157, v157, v158, vcc
	v_cmp_class_f32_e32 vcc, v149, v217
	s_nop 1
	v_cndmask_b32_e32 v149, v157, v149, vcc
	v_div_scale_f32 v156, s[26:27], v149, v149, 1.0
	v_rcp_f32_e32 v157, v156
	v_div_scale_f32 v158, vcc, 1.0, v149, 1.0
	v_fma_f32 v159, -v156, v157, 1.0
	v_fmac_f32_e32 v157, v159, v157
	v_mul_f32_e32 v159, v158, v157
	v_fma_f32 v160, -v156, v159, v158
	v_fmac_f32_e32 v159, v160, v157
	v_fma_f32 v156, -v156, v159, v158
	v_div_fmas_f32 v159, v156, v157, v159
	v_div_fixup_f32 v206, v159, v149, 1.0
	v_fmamk_f32 v150, v150, 0x3a800000, v216
	v_mul_f32_e32 v156, 0x4f800000, v150
	v_cmp_gt_f32_e32 vcc, s16, v150
	s_nop 1
	v_cndmask_b32_e32 v150, v150, v156, vcc
	v_sqrt_f32_e32 v157, v150
	s_nop 1
	v_add_u32_e32 v158, -1, v157
	v_add_u32_e32 v159, 1, v157
	v_fma_f32 v160, -v158, v157, v150
	v_fma_f32 v161, -v159, v157, v150
	v_cmp_ge_f32_e64 s[26:27], 0, v160
	s_nop 1
	v_cndmask_b32_e64 v157, v157, v158, s[26:27]
	v_cmp_lt_f32_e64 s[26:27], 0, v161
	s_nop 1
	v_cndmask_b32_e64 v157, v157, v159, s[26:27]
	v_mul_f32_e32 v158, 0x37800000, v157
	v_cndmask_b32_e32 v157, v157, v158, vcc
	v_cmp_class_f32_e32 vcc, v150, v217
	s_nop 1
	v_cndmask_b32_e32 v150, v157, v150, vcc
	v_div_scale_f32 v156, s[26:27], v150, v150, 1.0
	v_rcp_f32_e32 v157, v156
	v_div_scale_f32 v158, vcc, 1.0, v150, 1.0
	v_fma_f32 v159, -v156, v157, 1.0
	v_fmac_f32_e32 v157, v159, v157
	v_mul_f32_e32 v159, v158, v157
	v_fma_f32 v160, -v156, v159, v158
	v_fmac_f32_e32 v159, v160, v157
	v_fma_f32 v156, -v156, v159, v158
	v_div_fmas_f32 v159, v156, v157, v159
	v_div_fixup_f32 v208, v159, v150, 1.0
	v_fmamk_f32 v151, v151, 0x3a800000, v216
	v_mul_f32_e32 v156, 0x4f800000, v151
	v_cmp_gt_f32_e32 vcc, s16, v151
	s_nop 1
	v_cndmask_b32_e32 v151, v151, v156, vcc
	v_sqrt_f32_e32 v157, v151
	s_nop 1
	v_add_u32_e32 v158, -1, v157
	v_add_u32_e32 v159, 1, v157
	v_fma_f32 v160, -v158, v157, v151
	v_fma_f32 v161, -v159, v157, v151
	v_cmp_ge_f32_e64 s[26:27], 0, v160
	s_nop 1
	v_cndmask_b32_e64 v157, v157, v158, s[26:27]
	v_cmp_lt_f32_e64 s[26:27], 0, v161
	s_nop 1
	v_cndmask_b32_e64 v157, v157, v159, s[26:27]
	v_mul_f32_e32 v158, 0x37800000, v157
	v_cndmask_b32_e32 v157, v157, v158, vcc
	v_cmp_class_f32_e32 vcc, v151, v217
	s_nop 1
	v_cndmask_b32_e32 v151, v157, v151, vcc
	v_div_scale_f32 v156, s[26:27], v151, v151, 1.0
	v_rcp_f32_e32 v157, v156
	v_div_scale_f32 v158, vcc, 1.0, v151, 1.0
	v_fma_f32 v159, -v156, v157, 1.0
	v_fmac_f32_e32 v157, v159, v157
	v_mul_f32_e32 v159, v158, v157
	v_fma_f32 v160, -v156, v159, v158
	v_fmac_f32_e32 v159, v160, v157
	v_fma_f32 v156, -v156, v159, v158
	v_div_fmas_f32 v159, v156, v157, v159
	v_div_fixup_f32 v210, v159, v151, 1.0
	v_fmamk_f32 v152, v152, 0x3a800000, v216
	v_mul_f32_e32 v156, 0x4f800000, v152
	v_cmp_gt_f32_e32 vcc, s16, v152
	s_nop 1
	v_cndmask_b32_e32 v152, v152, v156, vcc
	v_sqrt_f32_e32 v157, v152
	s_nop 1
	v_add_u32_e32 v158, -1, v157
	v_add_u32_e32 v159, 1, v157
	v_fma_f32 v160, -v158, v157, v152
	v_fma_f32 v161, -v159, v157, v152
	v_cmp_ge_f32_e64 s[26:27], 0, v160
	s_nop 1
	v_cndmask_b32_e64 v157, v157, v158, s[26:27]
	v_cmp_lt_f32_e64 s[26:27], 0, v161
	s_nop 1
	v_cndmask_b32_e64 v157, v157, v159, s[26:27]
	v_mul_f32_e32 v158, 0x37800000, v157
	v_cndmask_b32_e32 v157, v157, v158, vcc
	v_cmp_class_f32_e32 vcc, v152, v217
	s_nop 1
	v_cndmask_b32_e32 v152, v157, v152, vcc
	v_div_scale_f32 v156, s[26:27], v152, v152, 1.0
	v_rcp_f32_e32 v157, v156
	v_div_scale_f32 v158, vcc, 1.0, v152, 1.0
	v_fma_f32 v159, -v156, v157, 1.0
	v_fmac_f32_e32 v157, v159, v157
	v_mul_f32_e32 v159, v158, v157
	v_fma_f32 v160, -v156, v159, v158
	v_fmac_f32_e32 v159, v160, v157
	v_fma_f32 v156, -v156, v159, v158
	v_div_fmas_f32 v159, v156, v157, v159
	v_div_fixup_f32 v212, v159, v152, 1.0
	v_fmamk_f32 v153, v153, 0x3a800000, v216
	v_mul_f32_e32 v156, 0x4f800000, v153
	v_cmp_gt_f32_e32 vcc, s16, v153
	s_nop 1
	v_cndmask_b32_e32 v153, v153, v156, vcc
	v_sqrt_f32_e32 v157, v153
	s_nop 1
	v_add_u32_e32 v158, -1, v157
	v_add_u32_e32 v159, 1, v157
	v_fma_f32 v160, -v158, v157, v153
	v_fma_f32 v161, -v159, v157, v153
	v_cmp_ge_f32_e64 s[26:27], 0, v160
	s_nop 1
	v_cndmask_b32_e64 v157, v157, v158, s[26:27]
	v_cmp_lt_f32_e64 s[26:27], 0, v161
	s_nop 1
	v_cndmask_b32_e64 v157, v157, v159, s[26:27]
	v_mul_f32_e32 v158, 0x37800000, v157
	v_cndmask_b32_e32 v157, v157, v158, vcc
	v_cmp_class_f32_e32 vcc, v153, v217
	s_nop 1
	v_cndmask_b32_e32 v153, v157, v153, vcc
	v_div_scale_f32 v156, s[26:27], v153, v153, 1.0
	v_rcp_f32_e32 v157, v156
	v_div_scale_f32 v158, vcc, 1.0, v153, 1.0
	v_fma_f32 v159, -v156, v157, 1.0
	v_fmac_f32_e32 v157, v159, v157
	v_mul_f32_e32 v159, v158, v157
	v_fma_f32 v160, -v156, v159, v158
	v_fmac_f32_e32 v159, v160, v157
	v_fma_f32 v156, -v156, v159, v158
	v_div_fmas_f32 v159, v156, v157, v159
	v_div_fixup_f32 v214, v159, v153, 1.0
	v_pk_mul_f32 v[124:125], v[124:125], v[200:201] op_sel_hi:[1,0]
	v_pk_mul_f32 v[126:127], v[126:127], v[200:201] op_sel_hi:[1,0]
	v_pk_mul_f32 v[124:125], v[184:185], v[124:125]
	v_pk_mul_f32 v[126:127], v[186:187], v[126:127]
	v_pk_mul_f32 v[96:97], v[96:97], v[200:201] op_sel_hi:[1,0]
	v_pk_mul_f32 v[98:99], v[98:99], v[200:201] op_sel_hi:[1,0]
	v_pk_mul_f32 v[96:97], v[188:189], v[96:97]
	v_pk_mul_f32 v[98:99], v[190:191], v[98:99]
	v_pk_mul_f32 v[64:65], v[64:65], v[200:201] op_sel_hi:[1,0]
	v_pk_mul_f32 v[66:67], v[66:67], v[200:201] op_sel_hi:[1,0]
	v_pk_mul_f32 v[64:65], v[192:193], v[64:65]
	v_pk_mul_f32 v[66:67], v[194:195], v[66:67]
	v_pk_mul_f32 v[44:45], v[44:45], v[200:201] op_sel_hi:[1,0]
	v_pk_mul_f32 v[46:47], v[46:47], v[200:201] op_sel_hi:[1,0]
	v_pk_mul_f32 v[44:45], v[196:197], v[44:45]
	v_pk_mul_f32 v[46:47], v[198:199], v[46:47]
	global_store_dwordx4 v128, v[124:127], s[8:9]
	global_store_dwordx4 v128, v[96:99], s[8:9] offset:64
	global_store_dwordx4 v128, v[64:67], s[8:9] offset:512
	global_store_dwordx4 v128, v[44:47], s[8:9] offset:576
	v_pk_mul_f32 v[120:121], v[120:121], v[202:203] op_sel_hi:[1,0]
	v_pk_mul_f32 v[122:123], v[122:123], v[202:203] op_sel_hi:[1,0]
	v_pk_mul_f32 v[120:121], v[184:185], v[120:121]
	v_pk_mul_f32 v[122:123], v[186:187], v[122:123]
	v_pk_mul_f32 v[88:89], v[88:89], v[202:203] op_sel_hi:[1,0]
	v_pk_mul_f32 v[90:91], v[90:91], v[202:203] op_sel_hi:[1,0]
	v_pk_mul_f32 v[88:89], v[188:189], v[88:89]
	v_pk_mul_f32 v[90:91], v[190:191], v[90:91]
	v_pk_mul_f32 v[56:57], v[56:57], v[202:203] op_sel_hi:[1,0]
	v_pk_mul_f32 v[58:59], v[58:59], v[202:203] op_sel_hi:[1,0]
	v_pk_mul_f32 v[56:57], v[192:193], v[56:57]
	v_pk_mul_f32 v[58:59], v[194:195], v[58:59]
	v_pk_mul_f32 v[36:37], v[36:37], v[202:203] op_sel_hi:[1,0]
	v_pk_mul_f32 v[38:39], v[38:39], v[202:203] op_sel_hi:[1,0]
	v_pk_mul_f32 v[36:37], v[196:197], v[36:37]
	v_pk_mul_f32 v[38:39], v[198:199], v[38:39]
	global_store_dwordx4 v129, v[120:123], s[8:9]
	global_store_dwordx4 v129, v[88:91], s[8:9] offset:64
	global_store_dwordx4 v129, v[56:59], s[8:9] offset:512
	global_store_dwordx4 v129, v[36:39], s[8:9] offset:576
	v_pk_mul_f32 v[116:117], v[116:117], v[204:205] op_sel_hi:[1,0]
	v_pk_mul_f32 v[118:119], v[118:119], v[204:205] op_sel_hi:[1,0]
	v_pk_mul_f32 v[116:117], v[184:185], v[116:117]
	v_pk_mul_f32 v[118:119], v[186:187], v[118:119]
	v_pk_mul_f32 v[84:85], v[84:85], v[204:205] op_sel_hi:[1,0]
	v_pk_mul_f32 v[86:87], v[86:87], v[204:205] op_sel_hi:[1,0]
	v_pk_mul_f32 v[84:85], v[188:189], v[84:85]
	v_pk_mul_f32 v[86:87], v[190:191], v[86:87]
	v_pk_mul_f32 v[52:53], v[52:53], v[204:205] op_sel_hi:[1,0]
	v_pk_mul_f32 v[54:55], v[54:55], v[204:205] op_sel_hi:[1,0]
	v_pk_mul_f32 v[52:53], v[192:193], v[52:53]
	v_pk_mul_f32 v[54:55], v[194:195], v[54:55]
	v_pk_mul_f32 v[28:29], v[28:29], v[204:205] op_sel_hi:[1,0]
	v_pk_mul_f32 v[30:31], v[30:31], v[204:205] op_sel_hi:[1,0]
	v_pk_mul_f32 v[28:29], v[196:197], v[28:29]
	v_pk_mul_f32 v[30:31], v[198:199], v[30:31]
	global_store_dwordx4 v130, v[116:119], s[8:9]
	global_store_dwordx4 v130, v[84:87], s[8:9] offset:64
	global_store_dwordx4 v130, v[52:55], s[8:9] offset:512
	global_store_dwordx4 v130, v[28:31], s[8:9] offset:576
	v_pk_mul_f32 v[112:113], v[112:113], v[206:207] op_sel_hi:[1,0]
	v_pk_mul_f32 v[114:115], v[114:115], v[206:207] op_sel_hi:[1,0]
	v_pk_mul_f32 v[112:113], v[184:185], v[112:113]
	v_pk_mul_f32 v[114:115], v[186:187], v[114:115]
	v_pk_mul_f32 v[80:81], v[80:81], v[206:207] op_sel_hi:[1,0]
	v_pk_mul_f32 v[82:83], v[82:83], v[206:207] op_sel_hi:[1,0]
	v_pk_mul_f32 v[80:81], v[188:189], v[80:81]
	v_pk_mul_f32 v[82:83], v[190:191], v[82:83]
	v_pk_mul_f32 v[48:49], v[48:49], v[206:207] op_sel_hi:[1,0]
	v_pk_mul_f32 v[50:51], v[50:51], v[206:207] op_sel_hi:[1,0]
	v_pk_mul_f32 v[48:49], v[192:193], v[48:49]
	v_pk_mul_f32 v[50:51], v[194:195], v[50:51]
	v_pk_mul_f32 v[20:21], v[20:21], v[206:207] op_sel_hi:[1,0]
	v_pk_mul_f32 v[22:23], v[22:23], v[206:207] op_sel_hi:[1,0]
	v_pk_mul_f32 v[20:21], v[196:197], v[20:21]
	v_pk_mul_f32 v[22:23], v[198:199], v[22:23]
	global_store_dwordx4 v131, v[112:115], s[8:9]
	global_store_dwordx4 v131, v[80:83], s[8:9] offset:64
	global_store_dwordx4 v131, v[48:51], s[8:9] offset:512
	global_store_dwordx4 v131, v[20:23], s[8:9] offset:576
	v_pk_mul_f32 v[108:109], v[108:109], v[208:209] op_sel_hi:[1,0]
	v_pk_mul_f32 v[110:111], v[110:111], v[208:209] op_sel_hi:[1,0]
	v_pk_mul_f32 v[108:109], v[184:185], v[108:109]
	v_pk_mul_f32 v[110:111], v[186:187], v[110:111]
	v_pk_mul_f32 v[76:77], v[76:77], v[208:209] op_sel_hi:[1,0]
	v_pk_mul_f32 v[78:79], v[78:79], v[208:209] op_sel_hi:[1,0]
	v_pk_mul_f32 v[76:77], v[188:189], v[76:77]
	v_pk_mul_f32 v[78:79], v[190:191], v[78:79]
	v_pk_mul_f32 v[40:41], v[40:41], v[208:209] op_sel_hi:[1,0]
	v_pk_mul_f32 v[42:43], v[42:43], v[208:209] op_sel_hi:[1,0]
	v_pk_mul_f32 v[40:41], v[192:193], v[40:41]
	v_pk_mul_f32 v[42:43], v[194:195], v[42:43]
	v_pk_mul_f32 v[12:13], v[12:13], v[208:209] op_sel_hi:[1,0]
	v_pk_mul_f32 v[14:15], v[14:15], v[208:209] op_sel_hi:[1,0]
	v_pk_mul_f32 v[12:13], v[196:197], v[12:13]
	v_pk_mul_f32 v[14:15], v[198:199], v[14:15]
	global_store_dwordx4 v132, v[108:111], s[8:9]
	global_store_dwordx4 v132, v[76:79], s[8:9] offset:64
	global_store_dwordx4 v132, v[40:43], s[8:9] offset:512
	global_store_dwordx4 v132, v[12:15], s[8:9] offset:576
	v_pk_mul_f32 v[104:105], v[104:105], v[210:211] op_sel_hi:[1,0]
	v_pk_mul_f32 v[106:107], v[106:107], v[210:211] op_sel_hi:[1,0]
	v_pk_mul_f32 v[104:105], v[184:185], v[104:105]
	v_pk_mul_f32 v[106:107], v[186:187], v[106:107]
	v_pk_mul_f32 v[72:73], v[72:73], v[210:211] op_sel_hi:[1,0]
	v_pk_mul_f32 v[74:75], v[74:75], v[210:211] op_sel_hi:[1,0]
	v_pk_mul_f32 v[72:73], v[188:189], v[72:73]
	v_pk_mul_f32 v[74:75], v[190:191], v[74:75]
	v_pk_mul_f32 v[32:33], v[32:33], v[210:211] op_sel_hi:[1,0]
	v_pk_mul_f32 v[34:35], v[34:35], v[210:211] op_sel_hi:[1,0]
	v_pk_mul_f32 v[32:33], v[192:193], v[32:33]
	v_pk_mul_f32 v[34:35], v[194:195], v[34:35]
	v_pk_mul_f32 v[8:9], v[8:9], v[210:211] op_sel_hi:[1,0]
	v_pk_mul_f32 v[10:11], v[10:11], v[210:211] op_sel_hi:[1,0]
	v_pk_mul_f32 v[8:9], v[196:197], v[8:9]
	v_pk_mul_f32 v[10:11], v[198:199], v[10:11]
	global_store_dwordx4 v133, v[104:107], s[8:9]
	global_store_dwordx4 v133, v[72:75], s[8:9] offset:64
	global_store_dwordx4 v133, v[32:35], s[8:9] offset:512
	global_store_dwordx4 v133, v[8:11], s[8:9] offset:576
	v_pk_mul_f32 v[100:101], v[100:101], v[212:213] op_sel_hi:[1,0]
	v_pk_mul_f32 v[102:103], v[102:103], v[212:213] op_sel_hi:[1,0]
	v_pk_mul_f32 v[100:101], v[184:185], v[100:101]
	v_pk_mul_f32 v[102:103], v[186:187], v[102:103]
	v_pk_mul_f32 v[68:69], v[68:69], v[212:213] op_sel_hi:[1,0]
	v_pk_mul_f32 v[70:71], v[70:71], v[212:213] op_sel_hi:[1,0]
	v_pk_mul_f32 v[68:69], v[188:189], v[68:69]
	v_pk_mul_f32 v[70:71], v[190:191], v[70:71]
	v_pk_mul_f32 v[24:25], v[24:25], v[212:213] op_sel_hi:[1,0]
	v_pk_mul_f32 v[26:27], v[26:27], v[212:213] op_sel_hi:[1,0]
	v_pk_mul_f32 v[24:25], v[192:193], v[24:25]
	v_pk_mul_f32 v[26:27], v[194:195], v[26:27]
	v_pk_mul_f32 v[4:5], v[4:5], v[212:213] op_sel_hi:[1,0]
	v_pk_mul_f32 v[6:7], v[6:7], v[212:213] op_sel_hi:[1,0]
	v_pk_mul_f32 v[4:5], v[196:197], v[4:5]
	v_pk_mul_f32 v[6:7], v[198:199], v[6:7]
	global_store_dwordx4 v134, v[100:103], s[8:9]
	global_store_dwordx4 v134, v[68:71], s[8:9] offset:64
	global_store_dwordx4 v134, v[24:27], s[8:9] offset:512
	global_store_dwordx4 v134, v[4:7], s[8:9] offset:576
	v_pk_mul_f32 v[92:93], v[92:93], v[214:215] op_sel_hi:[1,0]
	v_pk_mul_f32 v[94:95], v[94:95], v[214:215] op_sel_hi:[1,0]
	v_pk_mul_f32 v[92:93], v[184:185], v[92:93]
	v_pk_mul_f32 v[94:95], v[186:187], v[94:95]
	v_pk_mul_f32 v[60:61], v[60:61], v[214:215] op_sel_hi:[1,0]
	v_pk_mul_f32 v[62:63], v[62:63], v[214:215] op_sel_hi:[1,0]
	v_pk_mul_f32 v[60:61], v[188:189], v[60:61]
	v_pk_mul_f32 v[62:63], v[190:191], v[62:63]
	v_pk_mul_f32 v[16:17], v[16:17], v[214:215] op_sel_hi:[1,0]
	v_pk_mul_f32 v[18:19], v[18:19], v[214:215] op_sel_hi:[1,0]
	v_pk_mul_f32 v[16:17], v[192:193], v[16:17]
	v_pk_mul_f32 v[18:19], v[194:195], v[18:19]
	v_pk_mul_f32 v[0:1], v[0:1], v[214:215] op_sel_hi:[1,0]
	v_pk_mul_f32 v[2:3], v[2:3], v[214:215] op_sel_hi:[1,0]
	v_pk_mul_f32 v[0:1], v[196:197], v[0:1]
	v_pk_mul_f32 v[2:3], v[198:199], v[2:3]
	global_store_dwordx4 v135, v[92:95], s[8:9]
	global_store_dwordx4 v135, v[60:63], s[8:9] offset:64
	global_store_dwordx4 v135, v[16:19], s[8:9] offset:512
	global_store_dwordx4 v135, v[0:3], s[8:9] offset:576
	s_mov_b64 s[30:31], -1
	s_and_b64 vcc, exec, s[4:5]
	s_cbranch_vccnz .LBB0_1399
	s_andn2_b64 vcc, exec, s[12:13]
	s_cbranch_vccnz .LBB0_1398
	s_barrier
	s_branch .LBB0_1398
